# staggered: after all chains are done a WG whose next attention ticket is even runs one P7 output group before that unit (P7 overlaps attention of other WGs)
# baseline (speedup 1.0000x reference)
.LBB0_1077:
	v_mov_b32_e32 v255, 0
	v_cmp_eq_u32_e32 vcc, 0, v132
	s_and_saveexec_b64 s[8:9], vcc
	s_cbranch_execz .LBB0_1081
	s_mov_b64 s[12:13], exec
	v_mbcnt_lo_u32_b32 v2, s12, 0
	v_mbcnt_hi_u32_b32 v2, s13, v2
	v_cmp_eq_u32_e32 vcc, 0, v2
	s_and_saveexec_b64 s[10:11], vcc
	s_cbranch_execz .LBB0_1080
	s_load_dwordx2 s[14:15], s[26:27], 0x90
	s_bcnt1_i32_b64 s12, s[12:13]
	v_mov_b32_e32 v3, 0
	v_mov_b32_e32 v4, s12
	s_waitcnt lgkmcnt(0)
	global_atomic_add v3, v3, v4, s[14:15] offset:256 sc0
.LBB0_1080:
	s_or_b64 exec, exec, s[10:11]
	s_waitcnt vmcnt(0)
	v_readfirstlane_b32 s10, v3
	s_nop 1
	v_add_u32_e32 v2, s10, v2
	s_add_i32 s10, 0, 0x24180
	v_mov_b32_e32 v3, s10
	ds_write_b32 v3, v2
	v_mov_b32_e32 v2, 0
	ds_write_b32 v3, v2 offset:8

.Latt_reent:
	s_cmp_lt_u32 s40, 64
	v_and_b32_e32 v2, 63, v132
	s_cselect_b64 s[20:21], -1, 0
	s_add_i32 s22, 0, 0x19000
	v_ashrrev_i32_e32 v3, 3, v132
	v_lshlrev_b32_e32 v198, 3, v132
	v_lshl_add_u32 v207, v3, 2, s22
	s_add_i32 s55, 0, 0x15000
	v_lshlrev_b32_e32 v4, 8, v2
	s_add_i32 s78, 0, 0x24180
	v_cndmask_b32_e64 v3, 0, 1, s[20:21]
	s_mov_b32 s62, 0xffff0000
	v_mbcnt_hi_u32_b32 v1, -1, v1
	v_add_u32_e32 v201, 4, v2
	v_ashrrev_i32_e32 v199, 31, v198
	s_mov_b32 s29, 0
	v_cmp_eq_u32_e64 s[8:9], 0, v2
	v_cmp_gt_u32_e64 s[10:11], 2, v2
	v_cmp_gt_u32_e64 s[12:13], 4, v2
	v_cmp_gt_u32_e64 s[14:15], 8, v2
	v_cmp_gt_u32_e64 s[16:17], 16, v2
	v_cmp_gt_u32_e64 s[18:19], 32, v2
	v_lshl_add_u32 v206, v2, 2, s22
	v_lshl_add_u32 v208, v132, 5, s55
	v_mov_b32_e32 v209, s78
	s_movk_i32 s79, 0x1ff
	s_mov_b64 s[30:31], 0x300000
	v_cmp_ne_u32_e64 s[20:21], 1, v3
	v_lshlrev_b32_e32 v210, 2, v2
	v_mov_b32_e32 v3, 0
	v_add_u32_e32 v211, s55, v4
	s_mov_b32 s80, 0x42c00000
	s_mov_b64 s[34:35], 0x7000000
	s_mov_b64 s[36:37], 0x8000000
	s_mov_b64 s[38:39], 0x7010000
	s_mov_b64 s[40:41], 0x7020000
	s_mov_b64 s[42:43], 0x30000
	s_mov_b64 s[58:59], 0x10000
	s_mov_b64 s[60:61], 0x50000
	s_mov_b32 s63, -1
	s_mov_b32 s81, 0x41c00000
	s_mov_b64 s[64:65], 0x20000
	v_and_b32_e32 v236, 64, v1
	v_add_u32_e32 v212, -1, v1
	v_add_u32_e32 v213, -2, v1
	v_add_u32_e32 v214, -4, v1
	v_add_u32_e32 v215, -8, v1
	v_add_u32_e32 v216, -16, v1
	v_subrev_u32_e32 v217, 32, v1
	v_mov_b32_e32 v218, 0xff800000
	s_waitcnt lgkmcnt(0)
	s_barrier
	s_branch .LBB0_1084

.LBB0_1084:
	ds_read_b32 v2, v209
	ds_read_b32 v253, v209 offset:8
	s_mov_b64 s[22:23], -1
	s_waitcnt lgkmcnt(0)
	s_barrier
	v_cmp_lt_i32_e32 vcc, s79, v2
	v_readfirstlane_b32 s50, v2
	s_cbranch_vccnz .LBB0_1083
	v_readfirstlane_b32 s98, v253
	s_nop 0
	s_cmp_lg_u32 s98, 0
	s_cbranch_scc0 .Latt_cont
	s_bitcmp0_b32 s50, 0
	s_cbranch_scc1 .Lp7_mid
.Latt_cont:
	s_load_dwordx2 s[68:69], s[26:27], 0x90
	s_ashr_i32 s28, s50, 5
	s_sub_i32 s51, 16, s28
	s_lshl_b32 s22, s51, 8
	s_and_b32 s56, s50, 31
	v_cmp_gt_i32_e64 s[22:23], s22, v198
	v_mov_b32_e32 v4, 0
	v_mov_b32_e32 v5, 0
	s_waitcnt vmcnt(6)
	v_mov_b32_e32 v6, 0
	v_mov_b32_e32 v7, 0
	v_mov_b32_e32 v8, 0
	v_mov_b32_e32 v9, 0
	v_mov_b32_e32 v10, 0
	v_mov_b32_e32 v11, 0
	s_and_saveexec_b64 s[24:25], s[22:23]
	s_cbranch_execz .LBB0_1087
	s_lshl_b32 s57, s56, 14
	s_waitcnt lgkmcnt(0)
	s_add_u32 s66, s68, s57
	s_addc_u32 s67, s69, 0
	v_lshl_add_u64 v[4:5], v[198:199], 2, s[66:67]
	v_lshl_add_u64 v[6:7], v[4:5], 0, s[30:31]
	v_add_co_u32_e32 v4, vcc, 0x300000, v4
	s_nop 1
	v_addc_co_u32_e32 v5, vcc, 0, v5, vcc
	global_load_dwordx4 v[8:11], v[4:5], off
	s_nop 0
	global_load_dwordx4 v[4:7], v[6:7], off offset:16

.LBB0_1113:
	v_mov_b32_e32 v16, 0
	v_cmp_eq_u32_e64 s[22:23], 0, v230
	s_and_saveexec_b64 s[24:25], s[22:23]
	s_cbranch_execz .LBB0_1117
	s_mov_b64 s[72:73], exec
	v_mbcnt_lo_u32_b32 v2, s72, 0
	v_mbcnt_hi_u32_b32 v2, s73, v2
	v_cmp_eq_u32_e32 vcc, 0, v2
	s_and_saveexec_b64 s[70:71], vcc
	s_cbranch_execz .LBB0_1116
	s_bcnt1_i32_b64 s28, s[72:73]
	v_mov_b32_e32 v252, s28
	global_atomic_add v252, v3, v252, s[68:69] offset:256 sc0
	v_mov_b32_e32 v253, 0x1c00
	global_load_dword v251, v253, s[46:47] sc1

.LBB0_1120:
	v_add_f32_e32 v4, v66, v67
	v_add_f32_e32 v4, v68, v4
	v_add_f32_e32 v4, v69, v4
	v_add_f32_e32 v4, v70, v4
	v_add_f32_e32 v4, v71, v4
	v_add_f32_e32 v4, v72, v4
	v_add_f32_e32 v4, v73, v4
	v_add_f32_e32 v4, v74, v4
	v_add_f32_e32 v4, v75, v4
	v_add_f32_e32 v4, v76, v4
	v_add_f32_e32 v4, v77, v4
	v_add_f32_e32 v4, v78, v4
	v_add_f32_e32 v4, v79, v4
	v_add_f32_e32 v4, v80, v4
	v_add_f32_e32 v4, v81, v4
	v_add_f32_e32 v4, v4, v50
	v_add_f32_e32 v4, v51, v4
	v_add_f32_e32 v4, v52, v4
	v_add_f32_e32 v4, v53, v4
	v_add_f32_e32 v4, v54, v4
	v_add_f32_e32 v4, v55, v4
	v_add_f32_e32 v4, v56, v4
	v_add_f32_e32 v4, v57, v4
	v_add_f32_e32 v4, v58, v4
	v_add_f32_e32 v4, v59, v4
	v_add_f32_e32 v4, v60, v4
	v_add_f32_e32 v4, v61, v4
	v_add_f32_e32 v4, v62, v4
	v_add_f32_e32 v4, v63, v4
	v_add_f32_e32 v4, v64, v4
	v_add_f32_e32 v4, v65, v4
	v_add_f32_e32 v2, v2, v4
	v_cvt_pk_bf16_f32 v4, v66, v67
	v_cvt_pk_bf16_f32 v5, v68, v69
	v_cvt_pk_bf16_f32 v6, v70, v71
	v_cvt_pk_bf16_f32 v7, v72, v73
	v_cvt_pk_bf16_f32 v8, v74, v75
	v_cvt_pk_bf16_f32 v9, v76, v77
	v_cvt_pk_bf16_f32 v10, v78, v79
	v_cvt_pk_bf16_f32 v11, v80, v81
	v_cvt_pk_bf16_f32 v12, v50, v51
	v_cvt_pk_bf16_f32 v13, v52, v53
	v_cvt_pk_bf16_f32 v14, v54, v55
	v_cvt_pk_bf16_f32 v15, v56, v57
	v_cvt_pk_bf16_f32 v50, v58, v59
	v_cvt_pk_bf16_f32 v51, v60, v61
	v_cvt_pk_bf16_f32 v52, v62, v63
	v_cvt_pk_bf16_f32 v53, v64, v65
	s_cmp_lg_u32 0, -1
	s_cselect_b32 s24, 0, 0
	s_addk_i32 s24, 0x6000
	v_add3_u32 v17, v225, s24, v223
	v_add3_u32 v17, v17, v226, s87
	ds_read_b64_tr_b16 v[54:55],v17 offset:0
	ds_read_b64_tr_b16 v[56:57],v17 offset:512
	ds_read_b64_tr_b16 v[58:59],v17 offset:1024
	ds_read_b64_tr_b16 v[60:61],v17 offset:1536
	ds_read_b64_tr_b16 v[62:63],v17 offset:2048
	ds_read_b64_tr_b16 v[64:65],v17 offset:2560
	ds_read_b64_tr_b16 v[66:67],v17 offset:3072
	ds_read_b64_tr_b16 v[68:69],v17 offset:3584
	s_waitcnt lgkmcnt(0)
	s_nop 0
	v_mfma_f32_32x32x16_bf16 v[34:49], v[4:7], v[54:57], v[34:49]
	ds_read_b64_tr_b16 v[54:55],v17 offset:4096
	ds_read_b64_tr_b16 v[56:57],v17 offset:4608
	v_mfma_f32_32x32x16_bf16 v[34:49], v[8:11], v[58:61], v[34:49]
	ds_read_b64_tr_b16 v[58:59],v17 offset:5120
	ds_read_b64_tr_b16 v[60:61],v17 offset:5632
	v_mfma_f32_32x32x16_bf16 v[34:49], v[12:15], v[62:65], v[34:49]
	ds_read_b64_tr_b16 v[62:63],v17 offset:6144
	ds_read_b64_tr_b16 v[64:65],v17 offset:6656
	ds_read_b64_tr_b16 v[70:71],v17 offset:7168
	ds_read_b64_tr_b16 v[72:73],v17 offset:7680
	s_waitcnt lgkmcnt(0)
	v_mfma_f32_32x32x16_bf16 v[34:49], v[50:53], v[66:69], v[34:49]
	v_mfma_f32_32x32x16_bf16 v[18:33], v[4:7], v[54:57], v[18:33]
	v_mov_b32_e32 v4, v2
	s_nop 1
	v_permlane32_swap_b32_e32 v2, v4
	v_cmp_gt_u32_e32 vcc, 32, v219
	v_mfma_f32_32x32x16_bf16 v[18:33], v[8:11], v[58:61], v[18:33]
	v_mfma_f32_32x32x16_bf16 v[18:33], v[12:15], v[62:65], v[18:33]
	v_mfma_f32_32x32x16_bf16 v[18:33], v[50:53], v[70:73], v[18:33]
	s_and_saveexec_b64 s[24:25], vcc
	v_add_f32_e32 v2, v2, v4
	ds_write_b32 v228, v2 offset:49280
	s_or_b64 exec, exec, s[24:25]
	s_waitcnt lgkmcnt(0)
	ds_read_b128 v[4:7], v227 offset:49280
	ds_read_b128 v[8:11], v227 offset:49312
	s_lshl_b32 s24, s82, 12
	s_add_i32 s24, s24, 0
	v_lshlrev_b32_e32 v53, 9, v222
	s_waitcnt lgkmcnt(1)
	v_rcp_f32_e32 v2, v4
	v_rcp_f32_e32 v12, v5
	v_lshlrev_b32_e32 v54, 1, v221
	v_add3_u32 v53, s24, v53, v54
	v_mul_f32_e32 v34, v34, v2
	v_mul_f32_e32 v2, v18, v2
	v_cvt_pk_bf16_f32 v2, v2, s0
	v_rcp_f32_e32 v13, v6
	v_rcp_f32_e32 v14, v7
	s_waitcnt lgkmcnt(0)
	v_rcp_f32_e32 v15, v8
	ds_read_b128 v[4:7], v227 offset:49344
	v_rcp_f32_e32 v17, v9
	v_rcp_f32_e32 v50, v10
	v_rcp_f32_e32 v51, v11
	ds_read_b128 v[8:11], v227 offset:49376
	v_lshlrev_b32_e32 v52, 7, v224
	ds_write_b16 v53, v2 offset:51264
	v_mul_f32_e32 v2, v35, v12
	v_cvt_pk_bf16_f32 v2, v2, s0
	v_add3_u32 v18, s24, v52, v54
	ds_write_b16 v18, v2 offset:51328
	v_mul_f32_e32 v2, v19, v12
	v_cvt_pk_bf16_f32 v2, v2, s0
	ds_write_b16 v18, v2 offset:51392
	v_mul_f32_e32 v2, v36, v13
	v_cvt_pk_bf16_f32 v2, v2, s0
	ds_write_b16 v18, v2 offset:51456
	v_mul_f32_e32 v2, v20, v13
	v_cvt_pk_bf16_f32 v2, v2, s0
	ds_write_b16 v18, v2 offset:51520
	v_mul_f32_e32 v2, v37, v14
	v_cvt_pk_bf16_f32 v2, v2, s0
	ds_write_b16 v18, v2 offset:51584
	v_mul_f32_e32 v2, v21, v14
	v_cvt_pk_bf16_f32 v2, v2, s0
	ds_write_b16 v18, v2 offset:51648
	v_mul_f32_e32 v2, v38, v15
	v_cvt_pk_bf16_f32 v2, v2, s0
	ds_write_b16 v18, v2 offset:52224
	v_mul_f32_e32 v2, v22, v15
	v_cvt_pk_bf16_f32 v2, v2, s0
	ds_write_b16 v18, v2 offset:52288
	v_mul_f32_e32 v2, v39, v17
	v_cvt_pk_bf16_f32 v2, v2, s0
	ds_write_b16 v18, v2 offset:52352
	v_mul_f32_e32 v2, v23, v17
	v_cvt_pk_bf16_f32 v2, v2, s0
	ds_write_b16 v18, v2 offset:52416
	v_mul_f32_e32 v2, v40, v50
	v_cvt_pk_bf16_f32 v2, v2, s0
	ds_write_b16 v18, v2 offset:52480
	v_mul_f32_e32 v2, v24, v50
	v_cvt_pk_bf16_f32 v2, v2, s0
	s_waitcnt lgkmcnt(13)
	v_rcp_f32_e32 v4, v4
	ds_write_b16 v18, v2 offset:52544
	v_mul_f32_e32 v2, v41, v51
	v_cvt_pk_bf16_f32 v2, v2, s0
	ds_write_b16 v18, v2 offset:52608
	v_mul_f32_e32 v2, v25, v51
	v_cvt_pk_bf16_f32 v2, v2, s0
	v_rcp_f32_e32 v5, v5
	ds_write_b16 v18, v2 offset:52672
	v_mul_f32_e32 v2, v42, v4
	v_cvt_pk_bf16_f32 v2, v2, s0
	ds_write_b16 v18, v2 offset:53248
	v_mul_f32_e32 v2, v26, v4
	v_cvt_pk_bf16_f32 v2, v2, s0
	v_rcp_f32_e32 v6, v6
	ds_write_b16 v18, v2 offset:53312
	v_mul_f32_e32 v2, v43, v5
	v_cvt_pk_bf16_f32 v2, v2, s0
	ds_write_b16 v18, v2 offset:53376
	v_mul_f32_e32 v2, v27, v5
	v_cvt_pk_bf16_f32 v2, v2, s0
	v_rcp_f32_e32 v7, v7
	ds_write_b16 v18, v2 offset:53440
	v_mul_f32_e32 v2, v44, v6
	v_cvt_pk_bf16_f32 v2, v2, s0
	ds_write_b16 v18, v2 offset:53504
	v_mul_f32_e32 v2, v28, v6
	v_cvt_pk_bf16_f32 v2, v2, s0
	s_waitcnt lgkmcnt(14)
	v_rcp_f32_e32 v8, v8
	ds_write_b16 v18, v2 offset:53568
	v_mul_f32_e32 v2, v45, v7
	v_cvt_pk_bf16_f32 v2, v2, s0
	ds_write_b16 v18, v2 offset:53632
	v_mul_f32_e32 v2, v29, v7
	v_cvt_pk_bf16_f32 v2, v2, s0
	v_rcp_f32_e32 v9, v9
	ds_write_b16 v18, v2 offset:53696
	v_mul_f32_e32 v2, v46, v8
	v_cvt_pk_bf16_f32 v2, v2, s0
	ds_write_b16 v18, v2 offset:54272
	v_mul_f32_e32 v2, v30, v8
	v_cvt_pk_bf16_f32 v2, v2, s0
	v_rcp_f32_e32 v10, v10
	ds_write_b16 v18, v2 offset:54336
	v_mul_f32_e32 v2, v47, v9
	v_cvt_pk_bf16_f32 v2, v2, s0
	ds_write_b16 v18, v2 offset:54400
	v_mul_f32_e32 v2, v31, v9
	v_cvt_pk_bf16_f32 v2, v2, s0
	v_rcp_f32_e32 v11, v11
	ds_write_b16 v18, v2 offset:54464
	v_mul_f32_e32 v2, v48, v10
	v_cvt_pk_bf16_f32 v2, v2, s0
	ds_write_b16 v18, v2 offset:54528
	v_mul_f32_e32 v2, v32, v10
	v_cvt_pk_bf16_f32 v2, v2, s0
	ds_write_b16 v18, v2 offset:54592
	v_mul_f32_e32 v2, v49, v11
	v_cvt_pk_bf16_f32 v2, v2, s0
	ds_write_b16 v18, v2 offset:54656
	v_mul_f32_e32 v2, v33, v11
	v_cvt_pk_bf16_f32 v2, v2, s0
	ds_write_b16 v18, v2 offset:54720
	v_lshlrev_b32_e32 v2, 1, v220
	v_cvt_pk_bf16_f32 v34, v34, s0
	v_and_b32_e32 v2, 0x70, v2
	ds_write_b16 v53, v34 offset:51200
	v_lshrrev_b32_e32 v17, 3, v219
	v_add_u32_e32 v18, s24, v2
	s_waitcnt lgkmcnt(0)
	v_lshl_add_u64 v[12:13], s[66:67], 0, v[2:3]
	v_lshl_add_u32 v2, v17, 7, v18
	v_or_b32_e32 v19, 8, v17
	ds_read_b128 v[4:7], v2 offset:51200
	v_lshl_add_u32 v8, v19, 7, v18
	ds_read_b128 v[8:11], v8 offset:51200
	v_lshlrev_b32_e32 v2, 11, v17
	v_lshl_add_u64 v[14:15], v[12:13], 0, v[2:3]
	v_lshlrev_b32_e32 v2, 11, v19
	s_waitcnt lgkmcnt(1)
	global_store_dwordx4 v[14:15], v[4:7], off
	s_nop 1
	v_lshl_add_u64 v[4:5], v[12:13], 0, v[2:3]
	v_or_b32_e32 v2, 16, v17
	s_waitcnt lgkmcnt(0)
	global_store_dwordx4 v[4:5], v[8:11], off
	v_lshl_add_u32 v4, v2, 7, v18
	v_or_b32_e32 v17, 24, v17
	ds_read_b128 v[4:7], v4 offset:51200
	v_lshl_add_u32 v8, v17, 7, v18
	ds_read_b128 v[8:11], v8 offset:51200
	v_lshlrev_b32_e32 v2, 11, v2
	v_lshl_add_u64 v[14:15], v[12:13], 0, v[2:3]
	v_lshlrev_b32_e32 v2, 11, v17
	s_waitcnt lgkmcnt(1)
	global_store_dwordx4 v[14:15], v[4:7], off
	s_nop 1
	v_lshl_add_u64 v[4:5], v[12:13], 0, v[2:3]
	s_waitcnt lgkmcnt(0)
	global_store_dwordx4 v[4:5], v[8:11], off
	s_and_saveexec_b64 s[24:25], s[22:23]
	s_cbranch_execz .LBB0_1082
	s_waitcnt vmcnt(4)
	v_mov_b32_e32 v2, s78
	ds_write_b32 v2, v252
	v_cmp_lt_u32_e32 vcc, 63, v251
	s_nop 1
	v_cndmask_b32_e64 v253, 0, 1, vcc
	v_cmp_ne_u32_e32 vcc, -2, v255
	s_nop 1
	v_cndmask_b32_e32 v253, 0, v253, vcc
	ds_write_b32 v2, v253 offset:8
	s_branch .LBB0_1082

.Lp7_pull_init:
	s_and_b64 vcc, exec, s[4:5]
	s_cbranch_vccnz .LBB0_1177
	s_mov_b32 s99, s54
	v_mov_b32_e32 v255, -1

.Lp7_done:
	s_mov_b32 s54, s99
	v_readfirstlane_b32 s98, v255
	s_nop 0
	s_cmp_lt_i32 s98, 0
	s_cbranch_scc0 .Lp7_ret_dr
	s_mov_b64 s[8:9], -1
	s_branch .LBB0_1671
.Lp7_next:
	v_readfirstlane_b32 s98, v255
	s_nop 0
	s_cmp_lt_i32 s98, 0
	s_cbranch_scc1 .Lp7_pull
	s_mov_b32 s54, s99
	s_mov_b32 s98, 0
	s_branch .Lp7_ret
.Lp7_mid:
	s_cmp_lg_u64 s[4:5], 0
	s_cbranch_scc1 .Latt_cont
	v_mov_b32_e32 v255, s50
	s_mov_b32 s99, s54
	s_branch .Lp7_pull
.Lp7_ret_dr:
	s_mov_b32 s98, 1
.Lp7_ret:
	v_mov_b32_e32 v132, v0
	s_mov_b64 s[26:27], s[0:1]
	v_mbcnt_lo_u32_b32 v1, -1, 0
	s_nop 0
	v_readfirstlane_b32 s40, v132
	s_and_saveexec_b64 s[100:101], s[44:45]
	s_cbranch_execz .Lp7_ret2
	v_mov_b32_e32 v251, 0x24180
	v_mov_b32_e32 v250, 0
	ds_write_b32 v251, v255
	ds_write_b32 v251, v250 offset:8
.Lp7_ret2:
	s_or_b64 exec, exec, s[100:101]
	s_cmp_eq_u32 s98, 1
	s_cbranch_scc0 .Latt_reent
	v_mov_b32_e32 v255, -2
	s_branch .Latt_reent
